# v9: P8 residual epilogue with base loads 4 row-steps ahead (probe: best of 1/2/4/6/8/16), rest as v8
# baseline (speedup 1.0000x reference)
; __device__ __forceinline__ unsigned pk2(float lo, float hi) { f32x2 v = {lo, hi}; bf16x2_t b = __builtin_convertvector(v, bf16x2_t); return __builtin_bit_cast(unsigned, b); }
; __device__ __forceinline__ float bf_lo(unsigned u) { return __uint_as_float(u << 16); }
; __device__ __forceinline__ float bf_hi(unsigned u) { return __uint_as_float(u & 0xffff0000u); }
;     __device__ __forceinline__ void operator()(const AccT& acc, const Unit& u, int wr, int wc, int fr, int fq) const {
;         const int row0 = u.pm * BM + wr * 64 + fr; const int col0 = u.pn * BM + wc * 32 + 8 * fq; const int b = row0 >> 12;
;         f32x4 gt[2][2];
; #pragma unroll
;         for (int bj = 0; bj < 2; ++bj)
; #pragma unroll
;             for (int n = 0; n < 2; ++n) gt[bj][n] = *(const f32x4*)(gate + (size_t)b * NMOD + col0 + bj * HALF + n * 4);
; #pragma unroll
;         for (int ai = 0; ai < 2; ++ai)
; #pragma unroll
;             for (int m = 0; m < 4; ++m) { const size_t off = (size_t)(row0 + ai * HALF + m * 16) * DM + col0;
; #pragma unroll
;                 for (int bj = 0; bj < 2; ++bj) { f32x4 b0, b1;
;                     if constexpr (BB) { const u32x4 w = *(const u32x4*)((const bf16_t*)base + off + bj * HALF);
;                         b0 = (f32x4){bf_lo(w.x), bf_hi(w.x), bf_lo(w.y), bf_hi(w.y)}; b1 = (f32x4){bf_lo(w.z), bf_hi(w.z), bf_lo(w.w), bf_hi(w.w)}; }
;                     else { b0 = __builtin_nontemporal_load((const f32x4*)((const float*)base + off + bj * HALF)); b1 = __builtin_nontemporal_load((const f32x4*)((const float*)base + off + bj * HALF + 4)); }
;                     const f32x4 o0 = b0 + gt[bj][0] * acc[ai][bj][m][0], o1 = b1 + gt[bj][1] * acc[ai][bj][m][1];
;                     if constexpr (OB) { u32x4 w; w.x = pk2(o0[0], o0[1]); w.y = pk2(o0[2], o0[3]); w.z = pk2(o1[0], o1[1]); w.w = pk2(o1[2], o1[3]);
;                         *(u32x4*)((bf16_t*)out + off + bj * HALF) = w; }
;                     else { __builtin_nontemporal_store(o0, (f32x4*)((float*)out + off + bj * HALF)); __builtin_nontemporal_store(o1, (f32x4*)((float*)out + off + bj * HALF + 4)); } } }
.LBB0_769:
	s_lshl_b32 s24, s52, 8
	s_add_i32 s24, s24, s44
	v_or_b32_e32 v164, s24, v166
	v_lshl_or_b32 v162, s53, 8, v168
	s_ashr_i32 s24, s24, 12
	v_lshl_add_u32 v160, v164, 10, v162
	s_mul_hi_i32 s25, s24, 0x6000
	s_mulk_i32 s24, 0x6000
	v_lshlrev_b32_e32 v162, 2, v162
	s_add_u32 s24, s42, s24
	s_addc_u32 s25, s43, s25
	v_lshlrev_b32_e32 v161, 2, v160
	v_lshlrev_b32_e32 v160, 1, v160
	global_load_dwordx4 v[140:143], v162, s[24:25]
	global_load_dwordx4 v[136:139], v162, s[24:25] offset:16
	global_load_dwordx4 v[124:127], v162, s[24:25] offset:512
	global_load_dwordx4 v[120:123], v162, s[24:25] offset:528
	global_load_dwordx4 v[172:175], v160, s[8:9]
	global_load_dwordx4 v[176:179], v160, s[8:9] offset:256
	v_add_u32_e32 v160, 0x8000, v160
	global_load_dwordx4 v[180:183], v160, s[8:9]
	global_load_dwordx4 v[184:187], v160, s[8:9] offset:256
	s_waitcnt vmcnt(3)
	v_lshlrev_b32_e32 v162, 16, v172
	v_and_b32_e32 v163, 0xffff0000, v172
	v_lshlrev_b32_e32 v164, 16, v174
	v_and_b32_e32 v165, 0xffff0000, v174
	v_pk_fma_f32 v[132:133], v[132:133], v[140:141], v[162:163]
	v_pk_fma_f32 v[128:129], v[128:129], v[136:137], v[164:165]
	v_lshlrev_b32_e32 v162, 16, v173
	v_and_b32_e32 v163, 0xffff0000, v173
	v_lshlrev_b32_e32 v164, 16, v175
	v_and_b32_e32 v165, 0xffff0000, v175
	v_add_u32_e32 v160, 0x8000, v160
	global_load_dwordx4 v[172:175], v160, s[8:9]
	v_pk_fma_f32 v[134:135], v[134:135], v[142:143], v[162:163]
	v_pk_fma_f32 v[130:131], v[130:131], v[138:139], v[164:165]
	global_store_dwordx4 v161, v[132:135], s[64:65] nt
	global_store_dwordx4 v161, v[128:131], s[64:65] offset:16 nt
	s_waitcnt vmcnt(5)
	v_lshlrev_b32_e32 v162, 16, v176
	v_and_b32_e32 v163, 0xffff0000, v176
	v_lshlrev_b32_e32 v164, 16, v178
	v_and_b32_e32 v165, 0xffff0000, v178
	v_pk_fma_f32 v[116:117], v[116:117], v[124:125], v[162:163]
	v_pk_fma_f32 v[112:113], v[112:113], v[120:121], v[164:165]
	v_lshlrev_b32_e32 v162, 16, v177
	v_and_b32_e32 v163, 0xffff0000, v177
	v_lshlrev_b32_e32 v164, 16, v179
	v_and_b32_e32 v165, 0xffff0000, v179
	global_load_dwordx4 v[176:179], v160, s[8:9] offset:256
	v_pk_fma_f32 v[118:119], v[118:119], v[126:127], v[162:163]
	v_pk_fma_f32 v[114:115], v[114:115], v[122:123], v[164:165]
	global_store_dwordx4 v161, v[116:119], s[64:65] offset:512 nt
	global_store_dwordx4 v161, v[112:115], s[64:65] offset:528 nt
	v_add_u32_e32 v161, 0x10000, v161
	s_waitcnt vmcnt(7)
	v_lshlrev_b32_e32 v162, 16, v180
	v_and_b32_e32 v163, 0xffff0000, v180
	v_lshlrev_b32_e32 v164, 16, v182
	v_and_b32_e32 v165, 0xffff0000, v182
	v_pk_fma_f32 v[108:109], v[108:109], v[140:141], v[162:163]
	v_pk_fma_f32 v[104:105], v[104:105], v[136:137], v[164:165]
	v_lshlrev_b32_e32 v162, 16, v181
	v_and_b32_e32 v163, 0xffff0000, v181
	v_lshlrev_b32_e32 v164, 16, v183
	v_and_b32_e32 v165, 0xffff0000, v183
	v_add_u32_e32 v160, 0x8000, v160
	global_load_dwordx4 v[180:183], v160, s[8:9]
	v_pk_fma_f32 v[110:111], v[110:111], v[142:143], v[162:163]
	v_pk_fma_f32 v[106:107], v[106:107], v[138:139], v[164:165]
	global_store_dwordx4 v161, v[108:111], s[64:65] nt
	global_store_dwordx4 v161, v[104:107], s[64:65] offset:16 nt
	s_waitcnt vmcnt(9)
	v_lshlrev_b32_e32 v162, 16, v184
	v_and_b32_e32 v163, 0xffff0000, v184
	v_lshlrev_b32_e32 v164, 16, v186
	v_and_b32_e32 v165, 0xffff0000, v186
	v_pk_fma_f32 v[100:101], v[100:101], v[124:125], v[162:163]
	v_pk_fma_f32 v[96:97], v[96:97], v[120:121], v[164:165]
	v_lshlrev_b32_e32 v162, 16, v185
	v_and_b32_e32 v163, 0xffff0000, v185
	v_lshlrev_b32_e32 v164, 16, v187
	v_and_b32_e32 v165, 0xffff0000, v187
	global_load_dwordx4 v[184:187], v160, s[8:9] offset:256
	v_pk_fma_f32 v[102:103], v[102:103], v[126:127], v[162:163]
	v_pk_fma_f32 v[98:99], v[98:99], v[122:123], v[164:165]
	global_store_dwordx4 v161, v[100:103], s[64:65] offset:512 nt
	global_store_dwordx4 v161, v[96:99], s[64:65] offset:528 nt
	v_add_u32_e32 v161, 0x10000, v161
	s_waitcnt vmcnt(11)
	v_lshlrev_b32_e32 v162, 16, v172
	v_and_b32_e32 v163, 0xffff0000, v172
	v_lshlrev_b32_e32 v164, 16, v174
	v_and_b32_e32 v165, 0xffff0000, v174
	v_pk_fma_f32 v[92:93], v[92:93], v[140:141], v[162:163]
	v_pk_fma_f32 v[88:89], v[88:89], v[136:137], v[164:165]
	v_lshlrev_b32_e32 v162, 16, v173
	v_and_b32_e32 v163, 0xffff0000, v173
	v_lshlrev_b32_e32 v164, 16, v175
	v_and_b32_e32 v165, 0xffff0000, v175
	v_add_u32_e32 v160, 0x28000, v160
	global_load_dwordx4 v[172:175], v160, s[8:9]
	v_pk_fma_f32 v[94:95], v[94:95], v[142:143], v[162:163]
	v_pk_fma_f32 v[90:91], v[90:91], v[138:139], v[164:165]
	global_store_dwordx4 v161, v[92:95], s[64:65] nt
	global_store_dwordx4 v161, v[88:91], s[64:65] offset:16 nt
	s_waitcnt vmcnt(11)
	v_lshlrev_b32_e32 v162, 16, v176
	v_and_b32_e32 v163, 0xffff0000, v176
	v_lshlrev_b32_e32 v164, 16, v178
	v_and_b32_e32 v165, 0xffff0000, v178
	v_pk_fma_f32 v[84:85], v[84:85], v[124:125], v[162:163]
	v_pk_fma_f32 v[80:81], v[80:81], v[120:121], v[164:165]
	v_lshlrev_b32_e32 v162, 16, v177
	v_and_b32_e32 v163, 0xffff0000, v177
	v_lshlrev_b32_e32 v164, 16, v179
	v_and_b32_e32 v165, 0xffff0000, v179
	global_load_dwordx4 v[176:179], v160, s[8:9] offset:256
	v_pk_fma_f32 v[86:87], v[86:87], v[126:127], v[162:163]
	v_pk_fma_f32 v[82:83], v[82:83], v[122:123], v[164:165]
	global_store_dwordx4 v161, v[84:87], s[64:65] offset:512 nt
	global_store_dwordx4 v161, v[80:83], s[64:65] offset:528 nt
	v_add_u32_e32 v161, 0x10000, v161
	s_waitcnt vmcnt(11)
; __device__ __forceinline__ unsigned pk2(float lo, float hi) { f32x2 v = {lo, hi}; bf16x2_t b = __builtin_convertvector(v, bf16x2_t); return __builtin_bit_cast(unsigned, b); }
; __device__ __forceinline__ float bf_lo(unsigned u) { return __uint_as_float(u << 16); }
; __device__ __forceinline__ float bf_hi(unsigned u) { return __uint_as_float(u & 0xffff0000u); }
;     __device__ __forceinline__ void operator()(const AccT& acc, const Unit& u, int wr, int wc, int fr, int fq) const {
;     ...
;         for (int ai = 0; ai < 2; ++ai)
; #pragma unroll
;             for (int m = 0; m < 4; ++m) { const size_t off = (size_t)(row0 + ai * HALF + m * 16) * DM + col0;
; #pragma unroll
;                 for (int bj = 0; bj < 2; ++bj) { f32x4 b0, b1;
;                     if constexpr (BB) { const u32x4 w = *(const u32x4*)((const bf16_t*)base + off + bj * HALF);
;                         b0 = (f32x4){bf_lo(w.x), bf_hi(w.x), bf_lo(w.y), bf_hi(w.y)}; b1 = (f32x4){bf_lo(w.z), bf_hi(w.z), bf_lo(w.w), bf_hi(w.w)}; }
;                     else { b0 = __builtin_nontemporal_load((const f32x4*)((const float*)base + off + bj * HALF)); b1 = __builtin_nontemporal_load((const f32x4*)((const float*)base + off + bj * HALF + 4)); }
;                     const f32x4 o0 = b0 + gt[bj][0] * acc[ai][bj][m][0], o1 = b1 + gt[bj][1] * acc[ai][bj][m][1];
;                     if constexpr (OB) { u32x4 w; w.x = pk2(o0[0], o0[1]); w.y = pk2(o0[2], o0[3]); w.z = pk2(o1[0], o1[1]); w.w = pk2(o1[2], o1[3]);
;                         *(u32x4*)((bf16_t*)out + off + bj * HALF) = w; }
;                     else { __builtin_nontemporal_store(o0, (f32x4*)((float*)out + off + bj * HALF)); __builtin_nontemporal_store(o1, (f32x4*)((float*)out + off + bj * HALF + 4)); } } }
	v_lshlrev_b32_e32 v162, 16, v180
	v_and_b32_e32 v163, 0xffff0000, v180
	v_lshlrev_b32_e32 v164, 16, v182
	v_and_b32_e32 v165, 0xffff0000, v182
	v_pk_fma_f32 v[76:77], v[76:77], v[140:141], v[162:163]
	v_pk_fma_f32 v[72:73], v[72:73], v[136:137], v[164:165]
	v_lshlrev_b32_e32 v162, 16, v181
	v_and_b32_e32 v163, 0xffff0000, v181
	v_lshlrev_b32_e32 v164, 16, v183
	v_and_b32_e32 v165, 0xffff0000, v183
	v_add_u32_e32 v160, 0x8000, v160
	global_load_dwordx4 v[180:183], v160, s[8:9]
	v_pk_fma_f32 v[78:79], v[78:79], v[142:143], v[162:163]
	v_pk_fma_f32 v[74:75], v[74:75], v[138:139], v[164:165]
	global_store_dwordx4 v161, v[76:79], s[64:65] nt
	global_store_dwordx4 v161, v[72:75], s[64:65] offset:16 nt
	s_waitcnt vmcnt(11)
	v_lshlrev_b32_e32 v162, 16, v184
	v_and_b32_e32 v163, 0xffff0000, v184
	v_lshlrev_b32_e32 v164, 16, v186
	v_and_b32_e32 v165, 0xffff0000, v186
	v_pk_fma_f32 v[68:69], v[68:69], v[124:125], v[162:163]
	v_pk_fma_f32 v[64:65], v[64:65], v[120:121], v[164:165]
	v_lshlrev_b32_e32 v162, 16, v185
	v_and_b32_e32 v163, 0xffff0000, v185
	v_lshlrev_b32_e32 v164, 16, v187
	v_and_b32_e32 v165, 0xffff0000, v187
	global_load_dwordx4 v[184:187], v160, s[8:9] offset:256
	v_pk_fma_f32 v[70:71], v[70:71], v[126:127], v[162:163]
	v_pk_fma_f32 v[66:67], v[66:67], v[122:123], v[164:165]
	global_store_dwordx4 v161, v[68:71], s[64:65] offset:512 nt
	global_store_dwordx4 v161, v[64:67], s[64:65] offset:528 nt
	v_add_u32_e32 v161, 0x50000, v161
	s_waitcnt vmcnt(11)
	v_lshlrev_b32_e32 v162, 16, v172
	v_and_b32_e32 v163, 0xffff0000, v172
	v_lshlrev_b32_e32 v164, 16, v174
	v_and_b32_e32 v165, 0xffff0000, v174
	v_pk_fma_f32 v[60:61], v[60:61], v[140:141], v[162:163]
	v_pk_fma_f32 v[56:57], v[56:57], v[136:137], v[164:165]
	v_lshlrev_b32_e32 v162, 16, v173
	v_and_b32_e32 v163, 0xffff0000, v173
	v_lshlrev_b32_e32 v164, 16, v175
	v_and_b32_e32 v165, 0xffff0000, v175
	v_add_u32_e32 v160, 0x8000, v160
	global_load_dwordx4 v[172:175], v160, s[8:9]
	v_pk_fma_f32 v[62:63], v[62:63], v[142:143], v[162:163]
	v_pk_fma_f32 v[58:59], v[58:59], v[138:139], v[164:165]
	global_store_dwordx4 v161, v[60:63], s[64:65] nt
	global_store_dwordx4 v161, v[56:59], s[64:65] offset:16 nt
	s_waitcnt vmcnt(11)
	v_lshlrev_b32_e32 v162, 16, v176
	v_and_b32_e32 v163, 0xffff0000, v176
	v_lshlrev_b32_e32 v164, 16, v178
	v_and_b32_e32 v165, 0xffff0000, v178
	v_pk_fma_f32 v[52:53], v[52:53], v[124:125], v[162:163]
	v_pk_fma_f32 v[48:49], v[48:49], v[120:121], v[164:165]
	v_lshlrev_b32_e32 v162, 16, v177
	v_and_b32_e32 v163, 0xffff0000, v177
	v_lshlrev_b32_e32 v164, 16, v179
	v_and_b32_e32 v165, 0xffff0000, v179
	global_load_dwordx4 v[176:179], v160, s[8:9] offset:256
	v_pk_fma_f32 v[54:55], v[54:55], v[126:127], v[162:163]
	v_pk_fma_f32 v[50:51], v[50:51], v[122:123], v[164:165]
	global_store_dwordx4 v161, v[52:55], s[64:65] offset:512 nt
	global_store_dwordx4 v161, v[48:51], s[64:65] offset:528 nt
	v_add_u32_e32 v161, 0x10000, v161
	s_waitcnt vmcnt(11)
	v_lshlrev_b32_e32 v162, 16, v180
	v_and_b32_e32 v163, 0xffff0000, v180
	v_lshlrev_b32_e32 v164, 16, v182
	v_and_b32_e32 v165, 0xffff0000, v182
	v_pk_fma_f32 v[44:45], v[44:45], v[140:141], v[162:163]
	v_pk_fma_f32 v[40:41], v[40:41], v[136:137], v[164:165]
	v_lshlrev_b32_e32 v162, 16, v181
	v_and_b32_e32 v163, 0xffff0000, v181
	v_lshlrev_b32_e32 v164, 16, v183
	v_and_b32_e32 v165, 0xffff0000, v183
	v_add_u32_e32 v160, 0x8000, v160
	global_load_dwordx4 v[180:183], v160, s[8:9]
	v_pk_fma_f32 v[46:47], v[46:47], v[142:143], v[162:163]
	v_pk_fma_f32 v[42:43], v[42:43], v[138:139], v[164:165]
	global_store_dwordx4 v161, v[44:47], s[64:65] nt
	global_store_dwordx4 v161, v[40:43], s[64:65] offset:16 nt
	s_waitcnt vmcnt(11)
; __device__ __forceinline__ unsigned pk2(float lo, float hi) { f32x2 v = {lo, hi}; bf16x2_t b = __builtin_convertvector(v, bf16x2_t); return __builtin_bit_cast(unsigned, b); }
; __device__ __forceinline__ float bf_lo(unsigned u) { return __uint_as_float(u << 16); }
; __device__ __forceinline__ float bf_hi(unsigned u) { return __uint_as_float(u & 0xffff0000u); }
;     __device__ __forceinline__ void operator()(const AccT& acc, const Unit& u, int wr, int wc, int fr, int fq) const {
;     ...
;         for (int ai = 0; ai < 2; ++ai)
; #pragma unroll
;             for (int m = 0; m < 4; ++m) { const size_t off = (size_t)(row0 + ai * HALF + m * 16) * DM + col0;
; #pragma unroll
;                 for (int bj = 0; bj < 2; ++bj) { f32x4 b0, b1;
;                     if constexpr (BB) { const u32x4 w = *(const u32x4*)((const bf16_t*)base + off + bj * HALF);
;                         b0 = (f32x4){bf_lo(w.x), bf_hi(w.x), bf_lo(w.y), bf_hi(w.y)}; b1 = (f32x4){bf_lo(w.z), bf_hi(w.z), bf_lo(w.w), bf_hi(w.w)}; }
;                     else { b0 = __builtin_nontemporal_load((const f32x4*)((const float*)base + off + bj * HALF)); b1 = __builtin_nontemporal_load((const f32x4*)((const float*)base + off + bj * HALF + 4)); }
;                     const f32x4 o0 = b0 + gt[bj][0] * acc[ai][bj][m][0], o1 = b1 + gt[bj][1] * acc[ai][bj][m][1];
;                     if constexpr (OB) { u32x4 w; w.x = pk2(o0[0], o0[1]); w.y = pk2(o0[2], o0[3]); w.z = pk2(o1[0], o1[1]); w.w = pk2(o1[2], o1[3]);
;                         *(u32x4*)((bf16_t*)out + off + bj * HALF) = w; }
;                     else { __builtin_nontemporal_store(o0, (f32x4*)((float*)out + off + bj * HALF)); __builtin_nontemporal_store(o1, (f32x4*)((float*)out + off + bj * HALF + 4)); } } }
	v_lshlrev_b32_e32 v162, 16, v184
	v_and_b32_e32 v163, 0xffff0000, v184
	v_lshlrev_b32_e32 v164, 16, v186
	v_and_b32_e32 v165, 0xffff0000, v186
	v_pk_fma_f32 v[36:37], v[36:37], v[124:125], v[162:163]
	v_pk_fma_f32 v[32:33], v[32:33], v[120:121], v[164:165]
	v_lshlrev_b32_e32 v162, 16, v185
	v_and_b32_e32 v163, 0xffff0000, v185
	v_lshlrev_b32_e32 v164, 16, v187
	v_and_b32_e32 v165, 0xffff0000, v187
	global_load_dwordx4 v[184:187], v160, s[8:9] offset:256
	v_pk_fma_f32 v[38:39], v[38:39], v[126:127], v[162:163]
	v_pk_fma_f32 v[34:35], v[34:35], v[122:123], v[164:165]
	global_store_dwordx4 v161, v[36:39], s[64:65] offset:512 nt
	global_store_dwordx4 v161, v[32:35], s[64:65] offset:528 nt
	v_add_u32_e32 v161, 0x10000, v161
	s_waitcnt vmcnt(11)
	v_lshlrev_b32_e32 v162, 16, v172
	v_and_b32_e32 v163, 0xffff0000, v172
	v_lshlrev_b32_e32 v164, 16, v174
	v_and_b32_e32 v165, 0xffff0000, v174
	v_pk_fma_f32 v[28:29], v[28:29], v[140:141], v[162:163]
	v_pk_fma_f32 v[24:25], v[24:25], v[136:137], v[164:165]
	v_lshlrev_b32_e32 v162, 16, v173
	v_and_b32_e32 v163, 0xffff0000, v173
	v_lshlrev_b32_e32 v164, 16, v175
	v_and_b32_e32 v165, 0xffff0000, v175
	v_pk_fma_f32 v[30:31], v[30:31], v[142:143], v[162:163]
	v_pk_fma_f32 v[26:27], v[26:27], v[138:139], v[164:165]
	global_store_dwordx4 v161, v[28:31], s[64:65] nt
	global_store_dwordx4 v161, v[24:27], s[64:65] offset:16 nt
	s_waitcnt vmcnt(10)
	v_lshlrev_b32_e32 v162, 16, v176
	v_and_b32_e32 v163, 0xffff0000, v176
	v_lshlrev_b32_e32 v164, 16, v178
	v_and_b32_e32 v165, 0xffff0000, v178
	v_pk_fma_f32 v[20:21], v[20:21], v[124:125], v[162:163]
	v_pk_fma_f32 v[16:17], v[16:17], v[120:121], v[164:165]
	v_lshlrev_b32_e32 v162, 16, v177
	v_and_b32_e32 v163, 0xffff0000, v177
	v_lshlrev_b32_e32 v164, 16, v179
	v_and_b32_e32 v165, 0xffff0000, v179
	v_pk_fma_f32 v[22:23], v[22:23], v[126:127], v[162:163]
	v_pk_fma_f32 v[18:19], v[18:19], v[122:123], v[164:165]
	global_store_dwordx4 v161, v[20:23], s[64:65] offset:512 nt
	global_store_dwordx4 v161, v[16:19], s[64:65] offset:528 nt
	v_add_u32_e32 v161, 0x10000, v161
	s_waitcnt vmcnt(9)
	v_lshlrev_b32_e32 v162, 16, v180
	v_and_b32_e32 v163, 0xffff0000, v180
	v_lshlrev_b32_e32 v164, 16, v182
	v_and_b32_e32 v165, 0xffff0000, v182
	v_pk_fma_f32 v[12:13], v[12:13], v[140:141], v[162:163]
	v_pk_fma_f32 v[8:9], v[8:9], v[136:137], v[164:165]
	v_lshlrev_b32_e32 v162, 16, v181
	v_and_b32_e32 v163, 0xffff0000, v181
	v_lshlrev_b32_e32 v164, 16, v183
	v_and_b32_e32 v165, 0xffff0000, v183
	v_pk_fma_f32 v[14:15], v[14:15], v[142:143], v[162:163]
	v_pk_fma_f32 v[10:11], v[10:11], v[138:139], v[164:165]
	global_store_dwordx4 v161, v[12:15], s[64:65] nt
	global_store_dwordx4 v161, v[8:11], s[64:65] offset:16 nt
	s_waitcnt vmcnt(8)
	v_lshlrev_b32_e32 v162, 16, v184
	v_and_b32_e32 v163, 0xffff0000, v184
	v_lshlrev_b32_e32 v164, 16, v186
	v_and_b32_e32 v165, 0xffff0000, v186
	v_pk_fma_f32 v[4:5], v[4:5], v[124:125], v[162:163]
	v_pk_fma_f32 v[0:1], v[0:1], v[120:121], v[164:165]
	v_lshlrev_b32_e32 v162, 16, v185
	v_and_b32_e32 v163, 0xffff0000, v185
	v_lshlrev_b32_e32 v164, 16, v187
	v_and_b32_e32 v165, 0xffff0000, v187
	v_pk_fma_f32 v[6:7], v[6:7], v[126:127], v[162:163]
	v_pk_fma_f32 v[2:3], v[2:3], v[122:123], v[164:165]
	global_store_dwordx4 v161, v[4:7], s[64:65] offset:512 nt
	global_store_dwordx4 v161, v[0:3], s[64:65] offset:528 nt
	s_and_b64 vcc, exec, s[0:1]
	s_mov_b64 s[0:1], -1
	s_cbranch_vccnz .LBB0_754
	s_andn2_b64 vcc, exec, s[6:7]
	s_cbranch_vccnz .LBB0_753
	s_barrier
	s_branch .LBB0_753
